# grid barrier: one-hop release (the workgroup completing the cross-XCD count bumps every XCD generation word itself; XCD leaders no longer relay TOPGEN to their own word)
# speedup vs baseline: 1.0051x; 1.0042x over previous
; __device__ __forceinline__ unsigned xb_ld(unsigned* p)              { return __hip_atomic_load(p, __ATOMIC_RELAXED, __HIP_MEMORY_SCOPE_AGENT); }
; __device__ __forceinline__ unsigned xb_add(unsigned* p, unsigned v) { return __hip_atomic_fetch_add(p, v, __ATOMIC_RELAXED, __HIP_MEMORY_SCOPE_AGENT); }
; #define XB_SPIN(cond, bar) do { unsigned _sp = 0; while (cond) { __builtin_amdgcn_s_sleep(1); \
;     if ((++_sp & 255u) == 0u) { if (xb_ld(&(bar)[XB_TMO])) break; if (_sp > XB_SPIN_CAP) { atomicAdd(&(bar)[XB_TMO], 1u); break; } } } } while (0)
; __device__ __forceinline__ void xcd_barrier(const XcdBarrier& b) {
;     ...
;         const unsigned old = xb_add(&bar[XB_XSUB(b.x)], 1u);
;         const unsigned gen = old / nloc;
;         if (old + 1u == (gen + 1u) * nloc) {
;             __builtin_amdgcn_fence(__ATOMIC_RELEASE, "agent");
;             asm volatile("s_waitcnt vmcnt(0)" ::: "memory");
;             const unsigned og = xb_add(&bar[XB_TOP], 1u);
;             const unsigned tg = og / nx;
;             if (og + 1u == (tg + 1u) * nx) xb_add(&bar[XB_TOPGEN], 1u);
;             else XB_SPIN(xb_ld(&bar[XB_TOPGEN]) == tg, bar);
;             __builtin_amdgcn_fence(__ATOMIC_ACQUIRE, "agent");
;             xb_add(&bar[XB_XGEN(b.x)], 1u);
;             asm volatile("s_waitcnt vmcnt(0)" ::: "memory");
;         } else {
;             XB_SPIN(xb_ld(&bar[XB_XGEN(b.x)]) == gen, bar);
;             __builtin_amdgcn_fence(__ATOMIC_ACQUIRE, "agent");
;             asm volatile("s_waitcnt vmcnt(0)" ::: "memory");
;         }
.LBB0_174:
	s_or_b64 exec, exec, s[8:9]
	s_and_saveexec_b64 s[6:7], s[12:13]
	s_cbranch_execz .LBB0_176
	v_mov_b32_e32 v1, 1
	global_atomic_add v[2:3], v1, off
	v_add_co_u32_e32 v2, vcc, 0xffffef00, v2
	s_nop 1
	v_addc_co_u32_e32 v3, vcc, -1, v3, vcc
	global_atomic_add v[2:3], v1, off
	global_atomic_add v[2:3], v1, off offset:256
	global_atomic_add v[2:3], v1, off offset:512
	global_atomic_add v[2:3], v1, off offset:768
	global_atomic_add v[2:3], v1, off offset:1024
	global_atomic_add v[2:3], v1, off offset:1280
	global_atomic_add v[2:3], v1, off offset:1536
	global_atomic_add v[2:3], v1, off offset:1792
	global_atomic_add v[2:3], v1, off offset:2048
	global_atomic_add v[2:3], v1, off offset:2304
	global_atomic_add v[2:3], v1, off offset:2560
	global_atomic_add v[2:3], v1, off offset:2816
	global_atomic_add v[2:3], v1, off offset:3072
	global_atomic_add v[2:3], v1, off offset:3328
	global_atomic_add v[2:3], v1, off offset:3584
	global_atomic_add v[2:3], v1, off offset:3840
.LBB0_176:
	s_or_b64 exec, exec, s[6:7]
	s_mov_b64 s[6:7], exec
	v_mbcnt_lo_u32_b32 v1, s6, 0
	v_mbcnt_hi_u32_b32 v1, s7, v1
	s_mov_b32 s11, 0
	v_cmp_eq_u32_e32 vcc, 0, v1
	s_waitcnt vmcnt(0)
	s_and_saveexec_b64 s[8:9], vcc
	s_cbranch_execz .LBB0_178
	s_add_i32 s10, s28, 0x900
	s_lshl_b64 s[10:11], s[10:11], 2
	s_add_u32 s10, s26, s10
	s_addc_u32 s11, s27, s11
	s_bcnt1_i32_b64 s6, s[6:7]
	v_mov_b32_e32 v1, 0
	v_mov_b32_e32 v2, s6
.LBB0_178:
	s_or_b64 exec, exec, s[8:9]
	s_waitcnt vmcnt(0)

; __device__ __forceinline__ unsigned xb_ld(unsigned* p)              { return __hip_atomic_load(p, __ATOMIC_RELAXED, __HIP_MEMORY_SCOPE_AGENT); }
; __device__ __forceinline__ unsigned xb_add(unsigned* p, unsigned v) { return __hip_atomic_fetch_add(p, v, __ATOMIC_RELAXED, __HIP_MEMORY_SCOPE_AGENT); }
; #define XB_SPIN(cond, bar) do { unsigned _sp = 0; while (cond) { __builtin_amdgcn_s_sleep(1); \
;     if ((++_sp & 255u) == 0u) { if (xb_ld(&(bar)[XB_TMO])) break; if (_sp > XB_SPIN_CAP) { atomicAdd(&(bar)[XB_TMO], 1u); break; } } } } while (0)
; __device__ __forceinline__ void xcd_barrier(const XcdBarrier& b) {
;     ...
;         const unsigned old = xb_add(&bar[XB_XSUB(b.x)], 1u);
;         const unsigned gen = old / nloc;
;         if (old + 1u == (gen + 1u) * nloc) {
;             __builtin_amdgcn_fence(__ATOMIC_RELEASE, "agent");
;             asm volatile("s_waitcnt vmcnt(0)" ::: "memory");
;             const unsigned og = xb_add(&bar[XB_TOP], 1u);
;             const unsigned tg = og / nx;
;             if (og + 1u == (tg + 1u) * nx) xb_add(&bar[XB_TOPGEN], 1u);
;             else XB_SPIN(xb_ld(&bar[XB_TOPGEN]) == tg, bar);
;             __builtin_amdgcn_fence(__ATOMIC_ACQUIRE, "agent");
;             xb_add(&bar[XB_XGEN(b.x)], 1u);
;             asm volatile("s_waitcnt vmcnt(0)" ::: "memory");
;         } else {
;             XB_SPIN(xb_ld(&bar[XB_XGEN(b.x)]) == gen, bar);
;             __builtin_amdgcn_fence(__ATOMIC_ACQUIRE, "agent");
;             asm volatile("s_waitcnt vmcnt(0)" ::: "memory");
;         }
.LBB0_284:
	s_or_b64 exec, exec, s[8:9]
	s_and_saveexec_b64 s[6:7], s[12:13]
	s_cbranch_execz .LBB0_286
	v_mov_b32_e32 v4, 1
	global_atomic_add v[2:3], v4, off
	v_add_co_u32_e32 v2, vcc, 0xffffef00, v2
	s_nop 1
	v_addc_co_u32_e32 v3, vcc, -1, v3, vcc
	global_atomic_add v[2:3], v4, off
	global_atomic_add v[2:3], v4, off offset:256
	global_atomic_add v[2:3], v4, off offset:512
	global_atomic_add v[2:3], v4, off offset:768
	global_atomic_add v[2:3], v4, off offset:1024
	global_atomic_add v[2:3], v4, off offset:1280
	global_atomic_add v[2:3], v4, off offset:1536
	global_atomic_add v[2:3], v4, off offset:1792
	global_atomic_add v[2:3], v4, off offset:2048
	global_atomic_add v[2:3], v4, off offset:2304
	global_atomic_add v[2:3], v4, off offset:2560
	global_atomic_add v[2:3], v4, off offset:2816
	global_atomic_add v[2:3], v4, off offset:3072
	global_atomic_add v[2:3], v4, off offset:3328
	global_atomic_add v[2:3], v4, off offset:3584
	global_atomic_add v[2:3], v4, off offset:3840
.LBB0_286:
	s_or_b64 exec, exec, s[6:7]
	s_mov_b64 s[6:7], exec
	v_mbcnt_lo_u32_b32 v2, s6, 0
	v_mbcnt_hi_u32_b32 v2, s7, v2
	s_mov_b32 s11, 0
	v_cmp_eq_u32_e32 vcc, 0, v2
	s_waitcnt vmcnt(0)
	s_and_saveexec_b64 s[8:9], vcc
	s_cbranch_execz .LBB0_288
	s_add_i32 s10, s28, 0x900
	s_lshl_b64 s[10:11], s[10:11], 2
	s_add_u32 s10, s26, s10
	s_addc_u32 s11, s27, s11
	s_bcnt1_i32_b64 s6, s[6:7]
	v_mov_b32_e32 v2, 0
	v_mov_b32_e32 v3, s6
.LBB0_288:
	s_or_b64 exec, exec, s[8:9]
	s_waitcnt vmcnt(0)

; __device__ __forceinline__ unsigned xb_ld(unsigned* p)              { return __hip_atomic_load(p, __ATOMIC_RELAXED, __HIP_MEMORY_SCOPE_AGENT); }
; __device__ __forceinline__ unsigned xb_add(unsigned* p, unsigned v) { return __hip_atomic_fetch_add(p, v, __ATOMIC_RELAXED, __HIP_MEMORY_SCOPE_AGENT); }
; #define XB_SPIN(cond, bar) do { unsigned _sp = 0; while (cond) { __builtin_amdgcn_s_sleep(1); \
;     if ((++_sp & 255u) == 0u) { if (xb_ld(&(bar)[XB_TMO])) break; if (_sp > XB_SPIN_CAP) { atomicAdd(&(bar)[XB_TMO], 1u); break; } } } } while (0)
; __device__ __forceinline__ void xcd_barrier(const XcdBarrier& b) {
;     ...
;             const unsigned og = xb_add(&bar[XB_TOP], 1u);
;             const unsigned tg = og / nx;
;             if (og + 1u == (tg + 1u) * nx) xb_add(&bar[XB_TOPGEN], 1u);
;             else XB_SPIN(xb_ld(&bar[XB_TOPGEN]) == tg, bar);
;             __builtin_amdgcn_fence(__ATOMIC_ACQUIRE, "agent");
;             xb_add(&bar[XB_XGEN(b.x)], 1u);
;             asm volatile("s_waitcnt vmcnt(0)" ::: "memory");
.LBB0_385:
	s_or_b64 exec, exec, s[6:7]
	s_mov_b64 s[6:7], exec
	v_mbcnt_lo_u32_b32 v2, s6, 0
	v_mbcnt_hi_u32_b32 v2, s7, v2
	s_mov_b32 s11, 0
	v_cmp_eq_u32_e32 vcc, 0, v2
	s_waitcnt vmcnt(0)
	s_and_saveexec_b64 s[8:9], vcc
	s_cbranch_execz .LBB0_387
	s_add_i32 s10, s28, 0x900
	s_lshl_b64 s[10:11], s[10:11], 2
	s_add_u32 s10, s26, s10
	s_addc_u32 s11, s27, s11
	s_bcnt1_i32_b64 s6, s[6:7]
	v_mov_b32_e32 v2, 0
	v_mov_b32_e32 v3, s6
.LBB0_387:
	s_or_b64 exec, exec, s[8:9]
	s_waitcnt vmcnt(0)

; __device__ __forceinline__ unsigned xb_ld(unsigned* p)              { return __hip_atomic_load(p, __ATOMIC_RELAXED, __HIP_MEMORY_SCOPE_AGENT); }
; __device__ __forceinline__ unsigned xb_add(unsigned* p, unsigned v) { return __hip_atomic_fetch_add(p, v, __ATOMIC_RELAXED, __HIP_MEMORY_SCOPE_AGENT); }
; #define XB_SPIN(cond, bar) do { unsigned _sp = 0; while (cond) { __builtin_amdgcn_s_sleep(1); \
;     if ((++_sp & 255u) == 0u) { if (xb_ld(&(bar)[XB_TMO])) break; if (_sp > XB_SPIN_CAP) { atomicAdd(&(bar)[XB_TMO], 1u); break; } } } } while (0)
; __device__ __forceinline__ void xcd_barrier(const XcdBarrier& b) {
;     ...
;             const unsigned og = xb_add(&bar[XB_TOP], 1u);
;             const unsigned tg = og / nx;
;             if (og + 1u == (tg + 1u) * nx) xb_add(&bar[XB_TOPGEN], 1u);
;             else XB_SPIN(xb_ld(&bar[XB_TOPGEN]) == tg, bar);
;             __builtin_amdgcn_fence(__ATOMIC_ACQUIRE, "agent");
;             xb_add(&bar[XB_XGEN(b.x)], 1u);
;             asm volatile("s_waitcnt vmcnt(0)" ::: "memory");
.LBB0_666:
	s_or_b64 exec, exec, s[6:7]
	s_mov_b64 s[6:7], exec
	v_mbcnt_lo_u32_b32 v2, s6, 0
	v_mbcnt_hi_u32_b32 v2, s7, v2
	s_mov_b32 s11, 0
	v_cmp_eq_u32_e32 vcc, 0, v2
	s_waitcnt vmcnt(0)
	s_and_saveexec_b64 s[8:9], vcc
	s_cbranch_execz .LBB0_668
	s_add_i32 s10, s28, 0x900
	s_lshl_b64 s[10:11], s[10:11], 2
	s_add_u32 s10, s26, s10
	s_addc_u32 s11, s27, s11
	s_bcnt1_i32_b64 s6, s[6:7]
	v_mov_b32_e32 v2, 0
	v_mov_b32_e32 v3, s6
.LBB0_668:
	s_or_b64 exec, exec, s[8:9]
	s_waitcnt vmcnt(0)

; __device__ __forceinline__ unsigned xb_ld(unsigned* p)              { return __hip_atomic_load(p, __ATOMIC_RELAXED, __HIP_MEMORY_SCOPE_AGENT); }
; __device__ __forceinline__ unsigned xb_add(unsigned* p, unsigned v) { return __hip_atomic_fetch_add(p, v, __ATOMIC_RELAXED, __HIP_MEMORY_SCOPE_AGENT); }
; #define XB_SPIN(cond, bar) do { unsigned _sp = 0; while (cond) { __builtin_amdgcn_s_sleep(1); \
;     if ((++_sp & 255u) == 0u) { if (xb_ld(&(bar)[XB_TMO])) break; if (_sp > XB_SPIN_CAP) { atomicAdd(&(bar)[XB_TMO], 1u); break; } } } } while (0)
; __device__ __forceinline__ void xcd_barrier(const XcdBarrier& b) {
;     ...
;             const unsigned og = xb_add(&bar[XB_TOP], 1u);
;             const unsigned tg = og / nx;
;             if (og + 1u == (tg + 1u) * nx) xb_add(&bar[XB_TOPGEN], 1u);
;             else XB_SPIN(xb_ld(&bar[XB_TOPGEN]) == tg, bar);
;             __builtin_amdgcn_fence(__ATOMIC_ACQUIRE, "agent");
;             xb_add(&bar[XB_XGEN(b.x)], 1u);
;             asm volatile("s_waitcnt vmcnt(0)" ::: "memory");
.LBB0_1327:
	s_or_b64 exec, exec, s[6:7]
	s_mov_b64 s[6:7], exec
	v_mbcnt_lo_u32_b32 v2, s6, 0
	v_mbcnt_hi_u32_b32 v2, s7, v2
	s_mov_b32 s11, 0
	v_cmp_eq_u32_e32 vcc, 0, v2
	s_waitcnt vmcnt(0)
	s_and_saveexec_b64 s[8:9], vcc
	s_cbranch_execz .LBB0_1329
	s_add_i32 s10, s28, 0x900
	s_lshl_b64 s[10:11], s[10:11], 2
	s_add_u32 s10, s26, s10
	s_addc_u32 s11, s27, s11
	s_bcnt1_i32_b64 s6, s[6:7]
	v_mov_b32_e32 v2, 0
	v_mov_b32_e32 v3, s6
.LBB0_1329:
	s_or_b64 exec, exec, s[8:9]
	s_waitcnt vmcnt(0)

; __device__ __forceinline__ unsigned xb_ld(unsigned* p)              { return __hip_atomic_load(p, __ATOMIC_RELAXED, __HIP_MEMORY_SCOPE_AGENT); }
; __device__ __forceinline__ unsigned xb_add(unsigned* p, unsigned v) { return __hip_atomic_fetch_add(p, v, __ATOMIC_RELAXED, __HIP_MEMORY_SCOPE_AGENT); }
; #define XB_SPIN(cond, bar) do { unsigned _sp = 0; while (cond) { __builtin_amdgcn_s_sleep(1); \
;     if ((++_sp & 255u) == 0u) { if (xb_ld(&(bar)[XB_TMO])) break; if (_sp > XB_SPIN_CAP) { atomicAdd(&(bar)[XB_TMO], 1u); break; } } } } while (0)
; __device__ __forceinline__ void xcd_barrier(const XcdBarrier& b) {
;     ...
;             const unsigned og = xb_add(&bar[XB_TOP], 1u);
;             const unsigned tg = og / nx;
;             if (og + 1u == (tg + 1u) * nx) xb_add(&bar[XB_TOPGEN], 1u);
;             else XB_SPIN(xb_ld(&bar[XB_TOPGEN]) == tg, bar);
;             __builtin_amdgcn_fence(__ATOMIC_ACQUIRE, "agent");
;             xb_add(&bar[XB_XGEN(b.x)], 1u);
;             asm volatile("s_waitcnt vmcnt(0)" ::: "memory");
.LBB0_1482:
	s_or_b64 exec, exec, s[6:7]
	s_mov_b64 s[6:7], exec
	v_mbcnt_lo_u32_b32 v2, s6, 0
	v_mbcnt_hi_u32_b32 v2, s7, v2
	s_mov_b32 s11, 0
	v_cmp_eq_u32_e32 vcc, 0, v2
	s_waitcnt vmcnt(0)
	s_and_saveexec_b64 s[8:9], vcc
	s_cbranch_execz .LBB0_1484
	s_add_i32 s10, s28, 0x900
	s_lshl_b64 s[10:11], s[10:11], 2
	s_add_u32 s10, s26, s10
	s_addc_u32 s11, s27, s11
	s_bcnt1_i32_b64 s6, s[6:7]
	v_mov_b32_e32 v2, 0
	v_mov_b32_e32 v3, s6
.LBB0_1484:
	s_or_b64 exec, exec, s[8:9]
	s_waitcnt vmcnt(0)

; __device__ __forceinline__ unsigned xb_ld(unsigned* p)              { return __hip_atomic_load(p, __ATOMIC_RELAXED, __HIP_MEMORY_SCOPE_AGENT); }
; __device__ __forceinline__ unsigned xb_add(unsigned* p, unsigned v) { return __hip_atomic_fetch_add(p, v, __ATOMIC_RELAXED, __HIP_MEMORY_SCOPE_AGENT); }
; #define XB_SPIN(cond, bar) do { unsigned _sp = 0; while (cond) { __builtin_amdgcn_s_sleep(1); \
;     if ((++_sp & 255u) == 0u) { if (xb_ld(&(bar)[XB_TMO])) break; if (_sp > XB_SPIN_CAP) { atomicAdd(&(bar)[XB_TMO], 1u); break; } } } } while (0)
; __device__ __forceinline__ void xcd_barrier(const XcdBarrier& b) {
;     ...
;             const unsigned og = xb_add(&bar[XB_TOP], 1u);
;             const unsigned tg = og / nx;
;             if (og + 1u == (tg + 1u) * nx) xb_add(&bar[XB_TOPGEN], 1u);
;             else XB_SPIN(xb_ld(&bar[XB_TOPGEN]) == tg, bar);
;             __builtin_amdgcn_fence(__ATOMIC_ACQUIRE, "agent");
;             xb_add(&bar[XB_XGEN(b.x)], 1u);
;             asm volatile("s_waitcnt vmcnt(0)" ::: "memory");
.LBB0_1538:
	s_or_b64 exec, exec, s[6:7]
	s_mov_b64 s[6:7], exec
	v_mbcnt_lo_u32_b32 v2, s6, 0
	v_mbcnt_hi_u32_b32 v2, s7, v2
	s_mov_b32 s11, 0
	v_cmp_eq_u32_e32 vcc, 0, v2
	s_waitcnt vmcnt(0)
	s_and_saveexec_b64 s[8:9], vcc
	s_cbranch_execz .LBB0_1540
	s_add_i32 s10, s28, 0x900
	s_lshl_b64 s[10:11], s[10:11], 2
	s_add_u32 s10, s26, s10
	s_addc_u32 s11, s27, s11
	s_bcnt1_i32_b64 s6, s[6:7]
	v_mov_b32_e32 v2, 0
	v_mov_b32_e32 v3, s6
.LBB0_1540:
	s_or_b64 exec, exec, s[8:9]
	s_waitcnt vmcnt(0)

; __device__ __forceinline__ unsigned xb_ld(unsigned* p)              { return __hip_atomic_load(p, __ATOMIC_RELAXED, __HIP_MEMORY_SCOPE_AGENT); }
; __device__ __forceinline__ unsigned xb_add(unsigned* p, unsigned v) { return __hip_atomic_fetch_add(p, v, __ATOMIC_RELAXED, __HIP_MEMORY_SCOPE_AGENT); }
; #define XB_SPIN(cond, bar) do { unsigned _sp = 0; while (cond) { __builtin_amdgcn_s_sleep(1); \
;     if ((++_sp & 255u) == 0u) { if (xb_ld(&(bar)[XB_TMO])) break; if (_sp > XB_SPIN_CAP) { atomicAdd(&(bar)[XB_TMO], 1u); break; } } } } while (0)
; __device__ __forceinline__ void xcd_barrier(const XcdBarrier& b) {
;     ...
;         const unsigned old = xb_add(&bar[XB_XSUB(b.x)], 1u);
;         const unsigned gen = old / nloc;
;         if (old + 1u == (gen + 1u) * nloc) {
;             __builtin_amdgcn_fence(__ATOMIC_RELEASE, "agent");
;             asm volatile("s_waitcnt vmcnt(0)" ::: "memory");
;             const unsigned og = xb_add(&bar[XB_TOP], 1u);
;             const unsigned tg = og / nx;
;             if (og + 1u == (tg + 1u) * nx) xb_add(&bar[XB_TOPGEN], 1u);
;             else XB_SPIN(xb_ld(&bar[XB_TOPGEN]) == tg, bar);
;             __builtin_amdgcn_fence(__ATOMIC_ACQUIRE, "agent");
;             xb_add(&bar[XB_XGEN(b.x)], 1u);
;             asm volatile("s_waitcnt vmcnt(0)" ::: "memory");
;         } else {
;             XB_SPIN(xb_ld(&bar[XB_XGEN(b.x)]) == gen, bar);
;             __builtin_amdgcn_fence(__ATOMIC_ACQUIRE, "agent");
;             asm volatile("s_waitcnt vmcnt(0)" ::: "memory");
;         }
.LBB0_1648:
	s_or_b64 exec, exec, s[10:11]
	s_and_saveexec_b64 s[8:9], s[18:19]
	s_cbranch_execz .LBB0_1650
	v_mov_b32_e32 v4, 1
	global_atomic_add v[2:3], v4, off
	v_add_co_u32_e32 v2, vcc, 0xffffef00, v2
	s_nop 1
	v_addc_co_u32_e32 v3, vcc, -1, v3, vcc
	global_atomic_add v[2:3], v4, off
	global_atomic_add v[2:3], v4, off offset:256
	global_atomic_add v[2:3], v4, off offset:512
	global_atomic_add v[2:3], v4, off offset:768
	global_atomic_add v[2:3], v4, off offset:1024
	global_atomic_add v[2:3], v4, off offset:1280
	global_atomic_add v[2:3], v4, off offset:1536
	global_atomic_add v[2:3], v4, off offset:1792
	global_atomic_add v[2:3], v4, off offset:2048
	global_atomic_add v[2:3], v4, off offset:2304
	global_atomic_add v[2:3], v4, off offset:2560
	global_atomic_add v[2:3], v4, off offset:2816
	global_atomic_add v[2:3], v4, off offset:3072
	global_atomic_add v[2:3], v4, off offset:3328
	global_atomic_add v[2:3], v4, off offset:3584
	global_atomic_add v[2:3], v4, off offset:3840
.LBB0_1650:
	s_or_b64 exec, exec, s[8:9]
	s_mov_b64 s[8:9], exec
	v_mbcnt_lo_u32_b32 v2, s8, 0
	v_mbcnt_hi_u32_b32 v2, s9, v2
	s_mov_b32 s17, 0
	v_cmp_eq_u32_e32 vcc, 0, v2
	s_waitcnt vmcnt(0)
	s_and_saveexec_b64 s[10:11], vcc
	s_cbranch_execz .LBB0_1652
	s_add_i32 s16, s36, 0x900
	s_lshl_b64 s[16:17], s[16:17], 2
	s_add_u32 s16, s34, s16
	s_addc_u32 s17, s35, s17
	s_bcnt1_i32_b64 s8, s[8:9]
	v_mov_b32_e32 v2, 0
	v_mov_b32_e32 v3, s8
.LBB0_1652:
	s_or_b64 exec, exec, s[10:11]
	s_waitcnt vmcnt(0)

; __device__ __forceinline__ unsigned xb_ld(unsigned* p)              { return __hip_atomic_load(p, __ATOMIC_RELAXED, __HIP_MEMORY_SCOPE_AGENT); }
; __device__ __forceinline__ unsigned xb_add(unsigned* p, unsigned v) { return __hip_atomic_fetch_add(p, v, __ATOMIC_RELAXED, __HIP_MEMORY_SCOPE_AGENT); }
; #define XB_SPIN(cond, bar) do { unsigned _sp = 0; while (cond) { __builtin_amdgcn_s_sleep(1); \
;     if ((++_sp & 255u) == 0u) { if (xb_ld(&(bar)[XB_TMO])) break; if (_sp > XB_SPIN_CAP) { atomicAdd(&(bar)[XB_TMO], 1u); break; } } } } while (0)
; __device__ __forceinline__ void xcd_barrier(const XcdBarrier& b) {
;     ...
;             const unsigned og = xb_add(&bar[XB_TOP], 1u);
;             const unsigned tg = og / nx;
;             if (og + 1u == (tg + 1u) * nx) xb_add(&bar[XB_TOPGEN], 1u);
;             else XB_SPIN(xb_ld(&bar[XB_TOPGEN]) == tg, bar);
;             __builtin_amdgcn_fence(__ATOMIC_ACQUIRE, "agent");
;             xb_add(&bar[XB_XGEN(b.x)], 1u);
;             asm volatile("s_waitcnt vmcnt(0)" ::: "memory");
.LBB0_1796:
	s_or_b64 exec, exec, s[6:7]
	s_mov_b64 s[6:7], exec
	v_mbcnt_lo_u32_b32 v2, s6, 0
	v_mbcnt_hi_u32_b32 v2, s7, v2
	s_mov_b32 s11, 0
	v_cmp_eq_u32_e32 vcc, 0, v2
	s_waitcnt vmcnt(0)
	s_and_saveexec_b64 s[8:9], vcc
	s_cbranch_execz .LBB0_1798
	s_add_i32 s10, s28, 0x900
	s_lshl_b64 s[10:11], s[10:11], 2
	s_add_u32 s10, s26, s10
	s_addc_u32 s11, s27, s11
	s_bcnt1_i32_b64 s6, s[6:7]
	v_mov_b32_e32 v2, 0
	v_mov_b32_e32 v3, s6
.LBB0_1798:
	s_or_b64 exec, exec, s[8:9]
	s_waitcnt vmcnt(0)

; __device__ __forceinline__ unsigned xb_ld(unsigned* p)              { return __hip_atomic_load(p, __ATOMIC_RELAXED, __HIP_MEMORY_SCOPE_AGENT); }
; __device__ __forceinline__ unsigned xb_add(unsigned* p, unsigned v) { return __hip_atomic_fetch_add(p, v, __ATOMIC_RELAXED, __HIP_MEMORY_SCOPE_AGENT); }
; #define XB_SPIN(cond, bar) do { unsigned _sp = 0; while (cond) { __builtin_amdgcn_s_sleep(1); \
;     if ((++_sp & 255u) == 0u) { if (xb_ld(&(bar)[XB_TMO])) break; if (_sp > XB_SPIN_CAP) { atomicAdd(&(bar)[XB_TMO], 1u); break; } } } } while (0)
; __device__ __forceinline__ void xcd_barrier(const XcdBarrier& b) {
;     ...
;             const unsigned og = xb_add(&bar[XB_TOP], 1u);
;             const unsigned tg = og / nx;
;             if (og + 1u == (tg + 1u) * nx) xb_add(&bar[XB_TOPGEN], 1u);
;             else XB_SPIN(xb_ld(&bar[XB_TOPGEN]) == tg, bar);
;             __builtin_amdgcn_fence(__ATOMIC_ACQUIRE, "agent");
;             xb_add(&bar[XB_XGEN(b.x)], 1u);
;             asm volatile("s_waitcnt vmcnt(0)" ::: "memory");
.LBB0_1931:
	s_or_b64 exec, exec, s[6:7]
	s_mov_b64 s[6:7], exec
	v_mbcnt_lo_u32_b32 v2, s6, 0
	v_mbcnt_hi_u32_b32 v2, s7, v2
	s_mov_b32 s11, 0
	v_cmp_eq_u32_e32 vcc, 0, v2
	s_waitcnt vmcnt(0)
	s_and_saveexec_b64 s[8:9], vcc
	s_cbranch_execz .LBB0_1933
	s_add_i32 s10, s28, 0x900
	s_lshl_b64 s[10:11], s[10:11], 2
	s_add_u32 s10, s26, s10
	s_addc_u32 s11, s27, s11
	s_bcnt1_i32_b64 s6, s[6:7]
	v_mov_b32_e32 v2, 0
	v_mov_b32_e32 v3, s6
.LBB0_1933:
	s_or_b64 exec, exec, s[8:9]
	s_waitcnt vmcnt(0)

; __device__ __forceinline__ unsigned xb_ld(unsigned* p)              { return __hip_atomic_load(p, __ATOMIC_RELAXED, __HIP_MEMORY_SCOPE_AGENT); }
; __device__ __forceinline__ unsigned xb_add(unsigned* p, unsigned v) { return __hip_atomic_fetch_add(p, v, __ATOMIC_RELAXED, __HIP_MEMORY_SCOPE_AGENT); }
; #define XB_SPIN(cond, bar) do { unsigned _sp = 0; while (cond) { __builtin_amdgcn_s_sleep(1); \
;     if ((++_sp & 255u) == 0u) { if (xb_ld(&(bar)[XB_TMO])) break; if (_sp > XB_SPIN_CAP) { atomicAdd(&(bar)[XB_TMO], 1u); break; } } } } while (0)
; __device__ __forceinline__ void xcd_barrier(const XcdBarrier& b) {
;     ...
;             const unsigned og = xb_add(&bar[XB_TOP], 1u);
;             const unsigned tg = og / nx;
;             if (og + 1u == (tg + 1u) * nx) xb_add(&bar[XB_TOPGEN], 1u);
;             else XB_SPIN(xb_ld(&bar[XB_TOPGEN]) == tg, bar);
;             __builtin_amdgcn_fence(__ATOMIC_ACQUIRE, "agent");
;             xb_add(&bar[XB_XGEN(b.x)], 1u);
;             asm volatile("s_waitcnt vmcnt(0)" ::: "memory");
.LBB0_2102:
	s_or_b64 exec, exec, s[6:7]
	s_mov_b64 s[6:7], exec
	v_mbcnt_lo_u32_b32 v2, s6, 0
	v_mbcnt_hi_u32_b32 v2, s7, v2
	s_mov_b32 s11, 0
	v_cmp_eq_u32_e32 vcc, 0, v2
	s_waitcnt vmcnt(0)
	s_and_saveexec_b64 s[8:9], vcc
	s_cbranch_execz .LBB0_2104
	s_add_i32 s10, s28, 0x900
	s_lshl_b64 s[10:11], s[10:11], 2
	s_add_u32 s10, s26, s10
	s_addc_u32 s11, s27, s11
	s_bcnt1_i32_b64 s6, s[6:7]
	v_mov_b32_e32 v2, 0
	v_mov_b32_e32 v3, s6
.LBB0_2104:
	s_or_b64 exec, exec, s[8:9]
	s_waitcnt vmcnt(0)

; __device__ __forceinline__ unsigned xb_ld(unsigned* p)              { return __hip_atomic_load(p, __ATOMIC_RELAXED, __HIP_MEMORY_SCOPE_AGENT); }
; __device__ __forceinline__ unsigned xb_add(unsigned* p, unsigned v) { return __hip_atomic_fetch_add(p, v, __ATOMIC_RELAXED, __HIP_MEMORY_SCOPE_AGENT); }
; #define XB_SPIN(cond, bar) do { unsigned _sp = 0; while (cond) { __builtin_amdgcn_s_sleep(1); \
;     if ((++_sp & 255u) == 0u) { if (xb_ld(&(bar)[XB_TMO])) break; if (_sp > XB_SPIN_CAP) { atomicAdd(&(bar)[XB_TMO], 1u); break; } } } } while (0)
; __device__ __forceinline__ void xcd_barrier(const XcdBarrier& b) {
;     ...
;             const unsigned og = xb_add(&bar[XB_TOP], 1u);
;             const unsigned tg = og / nx;
;             if (og + 1u == (tg + 1u) * nx) xb_add(&bar[XB_TOPGEN], 1u);
;             else XB_SPIN(xb_ld(&bar[XB_TOPGEN]) == tg, bar);
;             __builtin_amdgcn_fence(__ATOMIC_ACQUIRE, "agent");
;             xb_add(&bar[XB_XGEN(b.x)], 1u);
;             asm volatile("s_waitcnt vmcnt(0)" ::: "memory");
.LBB0_2221:
	s_or_b64 exec, exec, s[6:7]
	s_mov_b64 s[6:7], exec
	v_mbcnt_lo_u32_b32 v2, s6, 0
	v_mbcnt_hi_u32_b32 v2, s7, v2
	s_mov_b32 s11, 0
	v_cmp_eq_u32_e32 vcc, 0, v2
	s_waitcnt vmcnt(0)
	s_and_saveexec_b64 s[8:9], vcc
	s_cbranch_execz .LBB0_2223
	s_add_i32 s10, s28, 0x900
	s_lshl_b64 s[10:11], s[10:11], 2
	s_add_u32 s10, s26, s10
	s_addc_u32 s11, s27, s11
	s_bcnt1_i32_b64 s6, s[6:7]
	v_mov_b32_e32 v2, 0
	v_mov_b32_e32 v3, s6
.LBB0_2223:
	s_or_b64 exec, exec, s[8:9]
	s_waitcnt vmcnt(0)

; __device__ __forceinline__ unsigned xb_ld(unsigned* p)              { return __hip_atomic_load(p, __ATOMIC_RELAXED, __HIP_MEMORY_SCOPE_AGENT); }
; __device__ __forceinline__ unsigned xb_add(unsigned* p, unsigned v) { return __hip_atomic_fetch_add(p, v, __ATOMIC_RELAXED, __HIP_MEMORY_SCOPE_AGENT); }
; #define XB_SPIN(cond, bar) do { unsigned _sp = 0; while (cond) { __builtin_amdgcn_s_sleep(1); \
;     if ((++_sp & 255u) == 0u) { if (xb_ld(&(bar)[XB_TMO])) break; if (_sp > XB_SPIN_CAP) { atomicAdd(&(bar)[XB_TMO], 1u); break; } } } } while (0)
; __device__ __forceinline__ void xcd_barrier(const XcdBarrier& b) {
;     ...
;             const unsigned og = xb_add(&bar[XB_TOP], 1u);
;             const unsigned tg = og / nx;
;             if (og + 1u == (tg + 1u) * nx) xb_add(&bar[XB_TOPGEN], 1u);
;             else XB_SPIN(xb_ld(&bar[XB_TOPGEN]) == tg, bar);
;             __builtin_amdgcn_fence(__ATOMIC_ACQUIRE, "agent");
;             xb_add(&bar[XB_XGEN(b.x)], 1u);
;             asm volatile("s_waitcnt vmcnt(0)" ::: "memory");
.LBB0_2502:
	s_or_b64 exec, exec, s[6:7]
	s_mov_b64 s[6:7], exec
	v_mbcnt_lo_u32_b32 v2, s6, 0
	v_mbcnt_hi_u32_b32 v2, s7, v2
	s_mov_b32 s11, 0
	v_cmp_eq_u32_e32 vcc, 0, v2
	s_waitcnt vmcnt(0)
	s_and_saveexec_b64 s[8:9], vcc
	s_cbranch_execz .LBB0_2504
	s_add_i32 s10, s28, 0x900
	s_lshl_b64 s[10:11], s[10:11], 2
	s_add_u32 s10, s26, s10
	s_addc_u32 s11, s27, s11
	s_bcnt1_i32_b64 s6, s[6:7]
	v_mov_b32_e32 v2, 0
	v_mov_b32_e32 v3, s6
.LBB0_2504:
	s_or_b64 exec, exec, s[8:9]
	s_waitcnt vmcnt(0)

; __device__ __forceinline__ unsigned xb_ld(unsigned* p)              { return __hip_atomic_load(p, __ATOMIC_RELAXED, __HIP_MEMORY_SCOPE_AGENT); }
; __device__ __forceinline__ unsigned xb_add(unsigned* p, unsigned v) { return __hip_atomic_fetch_add(p, v, __ATOMIC_RELAXED, __HIP_MEMORY_SCOPE_AGENT); }
; #define XB_SPIN(cond, bar) do { unsigned _sp = 0; while (cond) { __builtin_amdgcn_s_sleep(1); \
;     if ((++_sp & 255u) == 0u) { if (xb_ld(&(bar)[XB_TMO])) break; if (_sp > XB_SPIN_CAP) { atomicAdd(&(bar)[XB_TMO], 1u); break; } } } } while (0)
; __device__ __forceinline__ void xcd_barrier(const XcdBarrier& b) {
;     ...
;             const unsigned og = xb_add(&bar[XB_TOP], 1u);
;             const unsigned tg = og / nx;
;             if (og + 1u == (tg + 1u) * nx) xb_add(&bar[XB_TOPGEN], 1u);
;             else XB_SPIN(xb_ld(&bar[XB_TOPGEN]) == tg, bar);
;             __builtin_amdgcn_fence(__ATOMIC_ACQUIRE, "agent");
;             xb_add(&bar[XB_XGEN(b.x)], 1u);
;             asm volatile("s_waitcnt vmcnt(0)" ::: "memory");
.LBB0_3091:
	s_or_b64 exec, exec, s[6:7]
	s_mov_b64 s[6:7], exec
	v_mbcnt_lo_u32_b32 v2, s6, 0
	v_mbcnt_hi_u32_b32 v2, s7, v2
	s_mov_b32 s11, 0
	v_cmp_eq_u32_e32 vcc, 0, v2
	s_waitcnt vmcnt(0)
	s_and_saveexec_b64 s[8:9], vcc
	s_cbranch_execz .LBB0_3093
	s_add_i32 s10, s28, 0x900
	s_lshl_b64 s[10:11], s[10:11], 2
	s_add_u32 s10, s26, s10
	s_addc_u32 s11, s27, s11
	s_bcnt1_i32_b64 s6, s[6:7]
	v_mov_b32_e32 v2, 0
	v_mov_b32_e32 v3, s6
.LBB0_3093:
	s_or_b64 exec, exec, s[8:9]
	s_waitcnt vmcnt(0)

; __device__ __forceinline__ unsigned xb_ld(unsigned* p)              { return __hip_atomic_load(p, __ATOMIC_RELAXED, __HIP_MEMORY_SCOPE_AGENT); }
; __device__ __forceinline__ unsigned xb_add(unsigned* p, unsigned v) { return __hip_atomic_fetch_add(p, v, __ATOMIC_RELAXED, __HIP_MEMORY_SCOPE_AGENT); }
; #define XB_SPIN(cond, bar) do { unsigned _sp = 0; while (cond) { __builtin_amdgcn_s_sleep(1); \
;     if ((++_sp & 255u) == 0u) { if (xb_ld(&(bar)[XB_TMO])) break; if (_sp > XB_SPIN_CAP) { atomicAdd(&(bar)[XB_TMO], 1u); break; } } } } while (0)
; __device__ __forceinline__ void xcd_barrier(const XcdBarrier& b) {
;     ...
;         const unsigned old = xb_add(&bar[XB_XSUB(b.x)], 1u);
;         const unsigned gen = old / nloc;
;         if (old + 1u == (gen + 1u) * nloc) {
;             __builtin_amdgcn_fence(__ATOMIC_RELEASE, "agent");
;             asm volatile("s_waitcnt vmcnt(0)" ::: "memory");
;             const unsigned og = xb_add(&bar[XB_TOP], 1u);
;             const unsigned tg = og / nx;
;             if (og + 1u == (tg + 1u) * nx) xb_add(&bar[XB_TOPGEN], 1u);
;             else XB_SPIN(xb_ld(&bar[XB_TOPGEN]) == tg, bar);
;             __builtin_amdgcn_fence(__ATOMIC_ACQUIRE, "agent");
;             xb_add(&bar[XB_XGEN(b.x)], 1u);
;             asm volatile("s_waitcnt vmcnt(0)" ::: "memory");
;         } else {
;             XB_SPIN(xb_ld(&bar[XB_XGEN(b.x)]) == gen, bar);
;             __builtin_amdgcn_fence(__ATOMIC_ACQUIRE, "agent");
;             asm volatile("s_waitcnt vmcnt(0)" ::: "memory");
;         }
.LBB0_3202:
	s_or_b64 exec, exec, s[8:9]
	s_and_saveexec_b64 s[6:7], s[14:15]
	s_cbranch_execz .LBB0_3204
	v_mov_b32_e32 v4, 1
	global_atomic_add v[2:3], v4, off
	v_add_co_u32_e32 v2, vcc, 0xffffef00, v2
	s_nop 1
	v_addc_co_u32_e32 v3, vcc, -1, v3, vcc
	global_atomic_add v[2:3], v4, off
	global_atomic_add v[2:3], v4, off offset:256
	global_atomic_add v[2:3], v4, off offset:512
	global_atomic_add v[2:3], v4, off offset:768
	global_atomic_add v[2:3], v4, off offset:1024
	global_atomic_add v[2:3], v4, off offset:1280
	global_atomic_add v[2:3], v4, off offset:1536
	global_atomic_add v[2:3], v4, off offset:1792
	global_atomic_add v[2:3], v4, off offset:2048
	global_atomic_add v[2:3], v4, off offset:2304
	global_atomic_add v[2:3], v4, off offset:2560
	global_atomic_add v[2:3], v4, off offset:2816
	global_atomic_add v[2:3], v4, off offset:3072
	global_atomic_add v[2:3], v4, off offset:3328
	global_atomic_add v[2:3], v4, off offset:3584
	global_atomic_add v[2:3], v4, off offset:3840
.LBB0_3204:
	s_or_b64 exec, exec, s[6:7]
	s_mov_b64 s[6:7], exec
	v_mbcnt_lo_u32_b32 v2, s6, 0
	v_mbcnt_hi_u32_b32 v2, s7, v2
	s_mov_b32 s11, 0
	v_cmp_eq_u32_e32 vcc, 0, v2
	s_waitcnt vmcnt(0)
	s_and_saveexec_b64 s[8:9], vcc
	s_cbranch_execz .LBB0_3206
	s_add_i32 s10, s30, 0x900
	s_lshl_b64 s[10:11], s[10:11], 2
	s_add_u32 s10, s28, s10
	s_addc_u32 s11, s29, s11
	s_bcnt1_i32_b64 s6, s[6:7]
	v_mov_b32_e32 v2, 0
	v_mov_b32_e32 v3, s6
.LBB0_3206:
	s_or_b64 exec, exec, s[8:9]
	s_waitcnt vmcnt(0)

; __device__ __forceinline__ unsigned xb_ld(unsigned* p)              { return __hip_atomic_load(p, __ATOMIC_RELAXED, __HIP_MEMORY_SCOPE_AGENT); }
; __device__ __forceinline__ unsigned xb_add(unsigned* p, unsigned v) { return __hip_atomic_fetch_add(p, v, __ATOMIC_RELAXED, __HIP_MEMORY_SCOPE_AGENT); }
; #define XB_SPIN(cond, bar) do { unsigned _sp = 0; while (cond) { __builtin_amdgcn_s_sleep(1); \
;     if ((++_sp & 255u) == 0u) { if (xb_ld(&(bar)[XB_TMO])) break; if (_sp > XB_SPIN_CAP) { atomicAdd(&(bar)[XB_TMO], 1u); break; } } } } while (0)
; __device__ __forceinline__ void xcd_barrier(const XcdBarrier& b) {
;     ...
;             const unsigned og = xb_add(&bar[XB_TOP], 1u);
;             const unsigned tg = og / nx;
;             if (og + 1u == (tg + 1u) * nx) xb_add(&bar[XB_TOPGEN], 1u);
;             else XB_SPIN(xb_ld(&bar[XB_TOPGEN]) == tg, bar);
;             __builtin_amdgcn_fence(__ATOMIC_ACQUIRE, "agent");
;             xb_add(&bar[XB_XGEN(b.x)], 1u);
;             asm volatile("s_waitcnt vmcnt(0)" ::: "memory");
.LBB0_3304:
	s_or_b64 exec, exec, s[6:7]
	s_mov_b64 s[6:7], exec
	v_mbcnt_lo_u32_b32 v1, s6, 0
	v_mbcnt_hi_u32_b32 v1, s7, v1
	s_mov_b32 s11, 0
	v_cmp_eq_u32_e32 vcc, 0, v1
	s_waitcnt vmcnt(0)
	s_and_saveexec_b64 s[8:9], vcc
	s_cbranch_execz .LBB0_3306
	s_add_i32 s10, s28, 0x900
	s_lshl_b64 s[10:11], s[10:11], 2
	s_add_u32 s10, s26, s10
	s_addc_u32 s11, s27, s11
	s_bcnt1_i32_b64 s6, s[6:7]
	v_mov_b32_e32 v1, 0
	v_mov_b32_e32 v2, s6
.LBB0_3306:
	s_or_b64 exec, exec, s[8:9]
	s_waitcnt vmcnt(0)

; __device__ __forceinline__ unsigned xb_ld(unsigned* p)              { return __hip_atomic_load(p, __ATOMIC_RELAXED, __HIP_MEMORY_SCOPE_AGENT); }
; __device__ __forceinline__ unsigned xb_add(unsigned* p, unsigned v) { return __hip_atomic_fetch_add(p, v, __ATOMIC_RELAXED, __HIP_MEMORY_SCOPE_AGENT); }
; #define XB_SPIN(cond, bar) do { unsigned _sp = 0; while (cond) { __builtin_amdgcn_s_sleep(1); \
;     if ((++_sp & 255u) == 0u) { if (xb_ld(&(bar)[XB_TMO])) break; if (_sp > XB_SPIN_CAP) { atomicAdd(&(bar)[XB_TMO], 1u); break; } } } } while (0)
; __device__ __forceinline__ void xcd_barrier(const XcdBarrier& b) {
;     ...
;             const unsigned og = xb_add(&bar[XB_TOP], 1u);
;             const unsigned tg = og / nx;
;             if (og + 1u == (tg + 1u) * nx) xb_add(&bar[XB_TOPGEN], 1u);
;             else XB_SPIN(xb_ld(&bar[XB_TOPGEN]) == tg, bar);
;             __builtin_amdgcn_fence(__ATOMIC_ACQUIRE, "agent");
;             xb_add(&bar[XB_XGEN(b.x)], 1u);
;             asm volatile("s_waitcnt vmcnt(0)" ::: "memory");
.LBB0_3396:
	s_or_b64 exec, exec, s[6:7]
	s_mov_b64 s[6:7], exec
	v_mbcnt_lo_u32_b32 v1, s6, 0
	v_mbcnt_hi_u32_b32 v1, s7, v1
	s_mov_b32 s11, 0
	v_cmp_eq_u32_e32 vcc, 0, v1
	s_waitcnt vmcnt(0)
	s_and_saveexec_b64 s[8:9], vcc
	s_cbranch_execz .LBB0_3398
	s_add_i32 s10, s28, 0x900
	s_lshl_b64 s[10:11], s[10:11], 2
	s_add_u32 s10, s26, s10
	s_addc_u32 s11, s27, s11
	s_bcnt1_i32_b64 s6, s[6:7]
	v_mov_b32_e32 v1, 0
	v_mov_b32_e32 v2, s6
.LBB0_3398:
	s_or_b64 exec, exec, s[8:9]
	s_waitcnt vmcnt(0)
